# attention PV: pack P first, one base per d-tile with immediate offsets, 3-deep pipelined ds_read2 LDS reads; SSD output dsk*x batched LDS reads and counted vmcnt waits
# speedup vs baseline: 1.0104x; 1.0104x over previous
; DI u32x4 pack8(const float* f) { u32x4 w; w.x = pk2(f[0], f[1]); w.y = pk2(f[2], f[3]); w.z = pk2(f[4], f[5]); w.w = pk2(f[6], f[7]); return w; }
; DI void attn_item(const Params& p, const Ctx& c, int l, int S, int tokbase, int qb, int kvh) {
;     ...
;         mx = fmaxf(mx, __shfl_xor(mx, 16)); mx = fmaxf(mx, __shfl_xor(mx, 32));
;         float sum = 0.f;
; #pragma unroll
;         for (int t = 0; t < 17; ++t)
; #pragma unroll
;             for (int r = 0; r < 4; ++r) { const float pv = __builtin_amdgcn_exp2f(s[t][r] - mx); s[t][r] = pv; sum += pv; }
;         sum += __shfl_xor(sum, 16); sum += __shfl_xor(sum, 32);
;         sum += __builtin_amdgcn_exp2f(sink - mx);
;         f32x4 o[4];
; #pragma unroll
;         for (int dt = 0; dt < 4; ++dt) o[dt] = (f32x4){0.f, 0.f, 0.f, 0.f};
; #pragma unroll
;         for (int u = 0; u < 9; ++u) {
;             float g[8];
; #pragma unroll
;             for (int r = 0; r < 4; ++r) { g[r] = s[2 * u][r]; g[4 + r] = (2 * u + 1 < 17) ? s[(2 * u + 1 < 17) ? 2 * u + 1 : 0][r] : 0.f; }
;             const bf16x8 bfr = __builtin_bit_cast(bf16x8, pack8(g));
.LBB0_316:
	ds_bpermute_b32 v26, v104, v188
	v_max_f32_e32 v27, v188, v188
	v_add_u32_e32 v108, 0x900, v108
	v_add_u32_e32 v102, 0x100, v102
	s_waitcnt lgkmcnt(0)
	v_max_f32_e32 v26, v26, v26
	v_max_f32_e32 v26, v27, v26
	ds_bpermute_b32 v27, v105, v26
	s_waitcnt lgkmcnt(0)
	v_max_f32_e32 v27, v27, v27
	v_max_f32_e32 v27, v26, v27
	v_sub_f32_e32 v26, v186, v27
	v_exp_f32_e32 v26, v26
	v_sub_f32_e32 v28, v185, v27
	v_exp_f32_e32 v28, v28
	v_sub_f32_e32 v31, v187, v27
	v_add_f32_e32 v29, 0, v26
	v_exp_f32_e32 v48, v31
	v_add_f32_e32 v30, v28, v29
	v_sub_f32_e32 v29, v183, v27
	v_exp_f32_e32 v29, v29
	v_sub_f32_e32 v31, v182, v27
	v_exp_f32_e32 v63, v31
	v_sub_f32_e32 v31, v184, v27
	v_exp_f32_e32 v70, v31
	v_sub_f32_e32 v31, v173, v27
	v_add_f32_e32 v30, v29, v30
	v_exp_f32_e32 v72, v31
	v_sub_f32_e32 v31, v165, v27
	v_add_f32_e32 v30, v48, v30
	v_exp_f32_e32 v73, v31
	v_add_f32_e32 v30, v63, v30
	v_add_f32_e32 v30, v70, v30
	v_add_f32_e32 v30, v72, v30
	v_add_f32_e32 v31, v73, v30
	v_sub_f32_e32 v30, v160, v27
	v_exp_f32_e32 v30, v30
	v_sub_f32_e32 v37, v159, v27
	v_exp_f32_e32 v37, v37
	v_sub_f32_e32 v38, v158, v27
	v_add_f32_e32 v32, v30, v31
	v_sub_f32_e32 v31, v164, v27
	v_exp_f32_e32 v31, v31
	v_exp_f32_e32 v39, v38
	v_sub_f32_e32 v45, v152, v27
	v_exp_f32_e32 v45, v45
	v_add_f32_e32 v33, v31, v32
	v_sub_f32_e32 v32, v163, v27
	v_exp_f32_e32 v32, v32
	v_sub_f32_e32 v46, v150, v27
	v_exp_f32_e32 v50, v46
	v_sub_f32_e32 v47, v149, v27
	v_add_f32_e32 v34, v32, v33
	v_sub_f32_e32 v33, v162, v27
	v_exp_f32_e32 v33, v33
	v_exp_f32_e32 v49, v47
	v_sub_f32_e32 v47, v148, v27
	v_exp_f32_e32 v51, v47
	v_add_f32_e32 v35, v33, v34
	v_sub_f32_e32 v34, v156, v27
	v_exp_f32_e32 v34, v34
	v_sub_f32_e32 v47, v146, v27
	v_exp_f32_e32 v52, v47
	v_sub_f32_e32 v47, v137, v27
	v_add_f32_e32 v36, v34, v35
	v_sub_f32_e32 v35, v161, v27
	v_exp_f32_e32 v35, v35
	v_exp_f32_e32 v53, v47
	v_sub_f32_e32 v47, v145, v27
	v_exp_f32_e32 v54, v47
	v_add_f32_e32 v36, v35, v36
	v_add_f32_e32 v36, v37, v36
	v_add_f32_e32 v38, v39, v36
	v_sub_f32_e32 v36, v151, v27
	v_exp_f32_e32 v36, v36
	v_sub_f32_e32 v47, v143, v27
	v_exp_f32_e32 v56, v47
	v_sub_f32_e32 v47, v142, v27
	v_add_f32_e32 v40, v36, v38
	v_sub_f32_e32 v38, v157, v27
	v_exp_f32_e32 v38, v38
	v_exp_f32_e32 v58, v47
	v_sub_f32_e32 v47, v132, v27
	v_exp_f32_e32 v55, v47
	v_add_f32_e32 v41, v38, v40
	v_sub_f32_e32 v40, v155, v27
	v_exp_f32_e32 v40, v40
	v_sub_f32_e32 v47, v140, v27
	v_exp_f32_e32 v57, v47
	v_sub_f32_e32 v47, v139, v27
	v_add_f32_e32 v42, v40, v41
	v_sub_f32_e32 v41, v154, v27
	v_exp_f32_e32 v41, v41
	v_exp_f32_e32 v59, v47
	v_sub_f32_e32 v47, v138, v27
	v_exp_f32_e32 v60, v47
	v_add_f32_e32 v43, v41, v42
	v_sub_f32_e32 v42, v147, v27
	v_exp_f32_e32 v42, v42
	v_sub_f32_e32 v47, v128, v27
	v_exp_f32_e32 v61, v47
	v_sub_f32_e32 v47, v136, v27
	v_add_f32_e32 v44, v42, v43
	v_sub_f32_e32 v43, v153, v27
	v_exp_f32_e32 v43, v43
	v_exp_f32_e32 v62, v47
	v_sub_f32_e32 v47, v135, v27
	v_exp_f32_e32 v65, v47
	v_add_f32_e32 v44, v43, v44
	v_add_f32_e32 v44, v45, v44
	v_add_f32_e32 v46, v50, v44
	v_sub_f32_e32 v44, v141, v27
	v_exp_f32_e32 v44, v44
	v_sub_f32_e32 v47, v134, v27
	v_exp_f32_e32 v67, v47
	v_sub_f32_e32 v47, v119, v27
	v_add_f32_e32 v46, v44, v46
	v_add_f32_e32 v46, v49, v46
	v_add_f32_e32 v46, v51, v46
	v_add_f32_e32 v46, v52, v46
	v_add_f32_e32 v46, v53, v46
	v_add_f32_e32 v46, v54, v46
	v_add_f32_e32 v46, v56, v46
	v_add_f32_e32 v46, v58, v46
	v_add_f32_e32 v46, v55, v46
	v_add_f32_e32 v46, v57, v46
	v_add_f32_e32 v46, v59, v46
	v_add_f32_e32 v46, v60, v46
	v_add_f32_e32 v46, v61, v46
	v_exp_f32_e32 v64, v47
	v_sub_f32_e32 v47, v133, v27
	v_add_f32_e32 v46, v62, v46
	v_exp_f32_e32 v66, v47
	v_sub_f32_e32 v47, v131, v27
	v_add_f32_e32 v46, v65, v46
	v_exp_f32_e32 v68, v47
	v_sub_f32_e32 v47, v130, v27
	v_add_f32_e32 v46, v67, v46
	v_exp_f32_e32 v69, v47
	v_sub_f32_e32 v47, v103, v27
	v_add_f32_e32 v46, v64, v46
	v_exp_f32_e32 v71, v47
	v_sub_f32_e32 v47, v129, v27
	v_add_f32_e32 v46, v66, v46
	v_exp_f32_e32 v88, v47
	v_sub_f32_e32 v47, v127, v27
	v_add_f32_e32 v46, v68, v46
	v_exp_f32_e32 v89, v47
	v_sub_f32_e32 v47, v125, v27
	v_add_f32_e32 v46, v69, v46
	v_exp_f32_e32 v90, v47
	v_sub_f32_e32 v47, v97, v27
	v_add_f32_e32 v46, v71, v46
	v_exp_f32_e32 v91, v47
	v_sub_f32_e32 v47, v124, v27
	v_add_f32_e32 v46, v88, v46
	v_exp_f32_e32 v92, v47
	v_sub_f32_e32 v47, v120, v27
	v_add_f32_e32 v46, v89, v46
	v_exp_f32_e32 v93, v47
	v_sub_f32_e32 v47, v112, v27
	v_add_f32_e32 v46, v90, v46
	v_exp_f32_e32 v97, v47
	v_sub_f32_e32 v47, v96, v27
	v_add_f32_e32 v46, v91, v46
	v_exp_f32_e32 v96, v47
	v_sub_f32_e32 v47, v117, v27
	v_add_f32_e32 v46, v92, v46
	v_exp_f32_e32 v103, v47
	v_sub_f32_e32 v47, v113, v27
	v_add_f32_e32 v46, v93, v46
	v_exp_f32_e32 v112, v47
	v_sub_f32_e32 v47, v114, v27
	v_add_f32_e32 v46, v97, v46
	v_exp_f32_e32 v113, v47
	v_sub_f32_e32 v47, v94, v27
	v_add_f32_e32 v46, v96, v46
	v_exp_f32_e32 v94, v47
	v_sub_f32_e32 v47, v118, v27
	v_add_f32_e32 v46, v103, v46
	v_exp_f32_e32 v114, v47
	v_sub_f32_e32 v47, v115, v27
	v_add_f32_e32 v46, v112, v46
	v_exp_f32_e32 v115, v47
	v_sub_f32_e32 v47, v116, v27
	v_add_f32_e32 v46, v113, v46
	v_exp_f32_e32 v116, v47
	v_sub_f32_e32 v47, v95, v27
	v_add_f32_e32 v46, v94, v46
	v_exp_f32_e32 v95, v47
	v_sub_f32_e32 v47, v122, v27
	v_add_f32_e32 v46, v114, v46
	v_exp_f32_e32 v117, v47
	v_sub_f32_e32 v47, v123, v27
	v_add_f32_e32 v46, v115, v46
	v_exp_f32_e32 v118, v47
	v_sub_f32_e32 v47, v126, v27
	v_add_f32_e32 v46, v116, v46
	v_exp_f32_e32 v119, v47
	v_sub_f32_e32 v47, v110, v27
	v_add_f32_e32 v46, v95, v46
	v_exp_f32_e32 v110, v47
	v_sub_f32_e32 v47, v111, v27
	v_add_f32_e32 v46, v117, v46
	v_exp_f32_e32 v111, v47
	v_sub_f32_e32 v47, v121, v27
	v_add_f32_e32 v46, v118, v46
	v_exp_f32_e32 v120, v47
	v_sub_f32_e32 v47, v144, v27
	v_add_f32_e32 v46, v119, v46
	v_exp_f32_e32 v121, v47
	v_add_f32_e32 v46, v110, v46
	v_add_f32_e32 v46, v111, v46
	v_add_f32_e32 v46, v120, v46
	v_add_f32_e32 v46, v121, v46
	ds_bpermute_b32 v47, v104, v46
	v_sub_f32_e32 v27, v106, v27
	v_cvt_pk_bf16_f32 v130, v26, v28
	v_cvt_pk_bf16_f32 v131, v29, v48
	v_cvt_pk_bf16_f32 v132, v63, v70
	v_cvt_pk_bf16_f32 v133, v72, v73
	v_cvt_pk_bf16_f32 v134, v30, v31
	v_cvt_pk_bf16_f32 v135, v32, v33
	v_cvt_pk_bf16_f32 v136, v34, v35
	v_cvt_pk_bf16_f32 v137, v37, v39
	v_cvt_pk_bf16_f32 v138, v36, v38
	v_cvt_pk_bf16_f32 v139, v40, v41
	v_cvt_pk_bf16_f32 v140, v42, v43
	v_cvt_pk_bf16_f32 v141, v45, v50
	s_waitcnt lgkmcnt(0)
; #define LAS __attribute__((address_space(3)))
; DI u32x4 pack8(const float* f) { u32x4 w; w.x = pk2(f[0], f[1]); w.y = pk2(f[2], f[3]); w.z = pk2(f[4], f[5]); w.w = pk2(f[6], f[7]); return w; }
; DI void attn_item(const Params& p, const Ctx& c, int l, int S, int tokbase, int qb, int kvh) {
;     ...
;         sum += __shfl_xor(sum, 16); sum += __shfl_xor(sum, 32);
;         sum += __builtin_amdgcn_exp2f(sink - mx);
;         f32x4 o[4];
; #pragma unroll
;         for (int dt = 0; dt < 4; ++dt) o[dt] = (f32x4){0.f, 0.f, 0.f, 0.f};
; #pragma unroll
;         for (int u = 0; u < 9; ++u) {
;             float g[8];
; #pragma unroll
;             for (int r = 0; r < 4; ++r) { g[r] = s[2 * u][r]; g[4 + r] = (2 * u + 1 < 17) ? s[(2 * u + 1 < 17) ? 2 * u + 1 : 0][r] : 0.f; }
;             const bf16x8 bfr = __builtin_bit_cast(bf16x8, pack8(g));
; #pragma unroll
;             for (int dt = 0; dt < 4; ++dt) {
;                 const LAS bf16_t* vr = VTs + (dt * 16 + lr) * VP + (kt0 + 2 * u) * 16 + lg * 4;
;                 const s16x4 lo = *(const LAS s16x4*)vr;
;                 s16x4 hi = (s16x4){0, 0, 0, 0};
;                 if (2 * u + 1 < 17) hi = *(const LAS s16x4*)(vr + 16);
;                 o[dt] = __builtin_amdgcn_mfma_f32_16x16x32_bf16(__builtin_shufflevector(lo, hi, 0, 1, 2, 3, 4, 5, 6, 7), bfr, o[dt], 0, 0, 0); }
	v_add_f32_e32 v47, v46, v47
	v_exp_f32_e32 v46, v27
	ds_bpermute_b32 v122, v105, v47
	v_cvt_pk_bf16_f32 v142, v44, v49
	v_cvt_pk_bf16_f32 v143, v51, v52
	v_cvt_pk_bf16_f32 v144, v53, v54
	v_cvt_pk_bf16_f32 v145, v56, v58
	v_cvt_pk_bf16_f32 v146, v55, v57
	v_cvt_pk_bf16_f32 v147, v59, v60
	v_cvt_pk_bf16_f32 v148, v61, v62
	v_cvt_pk_bf16_f32 v149, v65, v67
	v_cvt_pk_bf16_f32 v150, v64, v66
	v_cvt_pk_bf16_f32 v151, v68, v69
	v_cvt_pk_bf16_f32 v152, v71, v88
	v_cvt_pk_bf16_f32 v153, v89, v90
	v_cvt_pk_bf16_f32 v154, v91, v92
	v_cvt_pk_bf16_f32 v155, v93, v97
	v_cvt_pk_bf16_f32 v156, v96, v103
	v_cvt_pk_bf16_f32 v157, v112, v113
	v_cvt_pk_bf16_f32 v158, v94, v114
	v_cvt_pk_bf16_f32 v159, v115, v116
	v_cvt_pk_bf16_f32 v160, v95, v117
	v_cvt_pk_bf16_f32 v161, v118, v119
	v_cvt_pk_bf16_f32 v162, v110, v111
	v_cvt_pk_bf16_f32 v163, v120, v121
	v_mov_b32_e32 v164, 0
	v_mov_b32_e32 v165, 0
	v_add_u32_e32 v123, 0xd800, v107
	v_add_u32_e32 v124, 0x10900, v107
	v_add_u32_e32 v125, 0x13a00, v107
	v_add_u32_e32 v126, 0x16b00, v107
	v_add_u32_e32 v107, 32, v107
	ds_read2_b64 v[48:51], v123 offset1:4
	ds_read2_b64 v[52:55], v124 offset1:4
	ds_read2_b64 v[56:59], v125 offset1:4
	ds_read2_b64 v[60:63], v126 offset1:4
	ds_read2_b64 v[64:67], v123 offset0:8 offset1:12
	ds_read2_b64 v[68:71], v124 offset0:8 offset1:12
	ds_read2_b64 v[72:75], v125 offset0:8 offset1:12
	ds_read2_b64 v[76:79], v126 offset0:8 offset1:12
	ds_read2_b64 v[80:83], v123 offset0:16 offset1:20
	ds_read2_b64 v[84:87], v124 offset0:16 offset1:20
	ds_read2_b64 v[88:91], v125 offset0:16 offset1:20
	ds_read2_b64 v[92:95], v126 offset0:16 offset1:20
	s_waitcnt lgkmcnt(8)
	v_add_f32_e32 v47, v47, v122
	v_mfma_f32_16x16x32_bf16 v[42:45], v[48:51], v[130:133], 0
	v_mfma_f32_16x16x32_bf16 v[38:41], v[52:55], v[130:133], 0
	v_mfma_f32_16x16x32_bf16 v[34:37], v[56:59], v[130:133], 0
	v_mfma_f32_16x16x32_bf16 v[26:29], v[60:63], v[130:133], 0
	ds_read2_b64 v[48:51], v123 offset0:24 offset1:28
	ds_read2_b64 v[52:55], v124 offset0:24 offset1:28
	ds_read2_b64 v[56:59], v125 offset0:24 offset1:28
	ds_read2_b64 v[60:63], v126 offset0:24 offset1:28
	s_waitcnt lgkmcnt(8)
	v_mfma_f32_16x16x32_bf16 v[42:45], v[64:67], v[134:137], v[42:45]
	v_mfma_f32_16x16x32_bf16 v[38:41], v[68:71], v[134:137], v[38:41]
	v_mfma_f32_16x16x32_bf16 v[34:37], v[72:75], v[134:137], v[34:37]
	v_mfma_f32_16x16x32_bf16 v[26:29], v[76:79], v[134:137], v[26:29]
	ds_read2_b64 v[64:67], v123 offset0:32 offset1:36
	ds_read2_b64 v[68:71], v124 offset0:32 offset1:36
	ds_read2_b64 v[72:75], v125 offset0:32 offset1:36
	ds_read2_b64 v[76:79], v126 offset0:32 offset1:36
	s_waitcnt lgkmcnt(8)
	v_mfma_f32_16x16x32_bf16 v[42:45], v[80:83], v[138:141], v[42:45]
	v_mfma_f32_16x16x32_bf16 v[38:41], v[84:87], v[138:141], v[38:41]
	v_mfma_f32_16x16x32_bf16 v[34:37], v[88:91], v[138:141], v[34:37]
	v_mfma_f32_16x16x32_bf16 v[26:29], v[92:95], v[138:141], v[26:29]
	ds_read2_b64 v[80:83], v123 offset0:40 offset1:44
	ds_read2_b64 v[84:87], v124 offset0:40 offset1:44
	ds_read2_b64 v[88:91], v125 offset0:40 offset1:44
	ds_read2_b64 v[92:95], v126 offset0:40 offset1:44
	s_waitcnt lgkmcnt(8)
	v_mfma_f32_16x16x32_bf16 v[42:45], v[48:51], v[142:145], v[42:45]
	v_mfma_f32_16x16x32_bf16 v[38:41], v[52:55], v[142:145], v[38:41]
	v_mfma_f32_16x16x32_bf16 v[34:37], v[56:59], v[142:145], v[34:37]
	v_mfma_f32_16x16x32_bf16 v[26:29], v[60:63], v[142:145], v[26:29]
	ds_read2_b64 v[48:51], v123 offset0:48 offset1:52
	ds_read2_b64 v[52:55], v124 offset0:48 offset1:52
	ds_read2_b64 v[56:59], v125 offset0:48 offset1:52
	ds_read2_b64 v[60:63], v126 offset0:48 offset1:52
	s_waitcnt lgkmcnt(8)
; #define LAS __attribute__((address_space(3)))
; DI unsigned pk2(float lo, float hi) { const f2_t v = {lo, hi}; const bf2_t r = __builtin_convertvector(v, bf2_t); return __builtin_bit_cast(unsigned, r); }
; DI u32x4 pack8(const float* f) { u32x4 w; w.x = pk2(f[0], f[1]); w.y = pk2(f[2], f[3]); w.z = pk2(f[4], f[5]); w.w = pk2(f[6], f[7]); return w; }
;     DI bf16_t* fOUTS() const { return (bf16_t*)(ws + WS_OUTS); }
; DI void attn_item(const Params& p, const Ctx& c, int l, int S, int tokbase, int qb, int kvh) {
;     ...
;         for (int u = 0; u < 9; ++u) {
;             float g[8];
; #pragma unroll
;             for (int r = 0; r < 4; ++r) { g[r] = s[2 * u][r]; g[4 + r] = (2 * u + 1 < 17) ? s[(2 * u + 1 < 17) ? 2 * u + 1 : 0][r] : 0.f; }
;             const bf16x8 bfr = __builtin_bit_cast(bf16x8, pack8(g));
; #pragma unroll
;             for (int dt = 0; dt < 4; ++dt) {
;                 const LAS bf16_t* vr = VTs + (dt * 16 + lr) * VP + (kt0 + 2 * u) * 16 + lg * 4;
;                 const s16x4 lo = *(const LAS s16x4*)vr;
;                 s16x4 hi = (s16x4){0, 0, 0, 0};
;                 if (2 * u + 1 < 17) hi = *(const LAS s16x4*)(vr + 16);
;                 o[dt] = __builtin_amdgcn_mfma_f32_16x16x32_bf16(__builtin_shufflevector(lo, hi, 0, 1, 2, 3, 4, 5, 6, 7), bfr, o[dt], 0, 0, 0); }
;         }
;         const float inv = 1.f / sum;
;         bf16_t* op = c.fOUTS() + (size_t)(tokbase + qpos) * OLD + head * 64 + lg * 4;
; #pragma unroll
;         for (int dt = 0; dt < 4; ++dt) { u32x2 ov; ov.x = pk2(o[dt][0] * inv, o[dt][1] * inv); ov.y = pk2(o[dt][2] * inv, o[dt][3] * inv); *(u32x2*)(op + dt * 16) = ov; }
	v_mfma_f32_16x16x32_bf16 v[42:45], v[64:67], v[146:149], v[42:45]
	v_mfma_f32_16x16x32_bf16 v[38:41], v[68:71], v[146:149], v[38:41]
	v_mfma_f32_16x16x32_bf16 v[34:37], v[72:75], v[146:149], v[34:37]
	v_mfma_f32_16x16x32_bf16 v[26:29], v[76:79], v[146:149], v[26:29]
	ds_read2_b64 v[64:67], v123 offset0:56 offset1:60
	ds_read2_b64 v[68:71], v124 offset0:56 offset1:60
	ds_read2_b64 v[72:75], v125 offset0:56 offset1:60
	ds_read2_b64 v[76:79], v126 offset0:56 offset1:60
	s_waitcnt lgkmcnt(8)
	v_mfma_f32_16x16x32_bf16 v[42:45], v[80:83], v[150:153], v[42:45]
	v_mfma_f32_16x16x32_bf16 v[38:41], v[84:87], v[150:153], v[38:41]
	v_mfma_f32_16x16x32_bf16 v[34:37], v[88:91], v[150:153], v[34:37]
	v_mfma_f32_16x16x32_bf16 v[26:29], v[92:95], v[150:153], v[26:29]
	ds_read_b64 v[80:81], v123 offset:512
	ds_read_b64 v[84:85], v124 offset:512
	ds_read_b64 v[88:89], v125 offset:512
	ds_read_b64 v[92:93], v126 offset:512
	v_mov_b64_e32 v[82:83], 0
	v_mov_b64_e32 v[86:87], 0
	v_mov_b64_e32 v[90:91], 0
	v_mov_b64_e32 v[94:95], 0
	s_waitcnt lgkmcnt(8)
	v_mfma_f32_16x16x32_bf16 v[42:45], v[48:51], v[154:157], v[42:45]
	v_mfma_f32_16x16x32_bf16 v[38:41], v[52:55], v[154:157], v[38:41]
	v_mfma_f32_16x16x32_bf16 v[34:37], v[56:59], v[154:157], v[34:37]
	v_mfma_f32_16x16x32_bf16 v[26:29], v[60:63], v[154:157], v[26:29]
	s_waitcnt lgkmcnt(4)
	v_mfma_f32_16x16x32_bf16 v[42:45], v[64:67], v[158:161], v[42:45]
	v_mfma_f32_16x16x32_bf16 v[38:41], v[68:71], v[158:161], v[38:41]
	v_mfma_f32_16x16x32_bf16 v[34:37], v[72:75], v[158:161], v[34:37]
	v_mfma_f32_16x16x32_bf16 v[26:29], v[76:79], v[158:161], v[26:29]
	s_waitcnt lgkmcnt(0)
	v_mfma_f32_16x16x32_bf16 v[42:45], v[80:83], v[162:165], v[42:45]
	v_mfma_f32_16x16x32_bf16 v[38:41], v[84:87], v[162:165], v[38:41]
	v_mfma_f32_16x16x32_bf16 v[34:37], v[88:91], v[162:165], v[34:37]
	v_mfma_f32_16x16x32_bf16 v[26:29], v[92:95], v[162:165], v[26:29]
	v_add_f32_e32 v30, v46, v47
	v_div_scale_f32 v31, s[20:21], v30, v30, 1.0
	v_rcp_f32_e32 v32, v31
	s_nop 0
	v_fma_f32 v33, -v31, v32, 1.0
	v_fmac_f32_e32 v32, v33, v32
	v_div_scale_f32 v33, vcc, 1.0, v30, 1.0
	v_mul_f32_e32 v46, v33, v32
	v_fma_f32 v47, -v31, v46, v33
	v_fmac_f32_e32 v46, v47, v32
	v_fma_f32 v31, -v31, v46, v33
	v_div_fmas_f32 v31, v31, v32, v46
	v_div_fixup_f32 v30, v31, v30, 1.0
	v_add_u32_e32 v31, s40, v1
	v_pk_mul_f32 v[42:43], v[30:31], v[42:43] op_sel_hi:[0,1]
	v_pk_mul_f32 v[44:45], v[30:31], v[44:45] op_sel_hi:[0,1]
	v_pk_mul_f32 v[38:39], v[30:31], v[38:39] op_sel_hi:[0,1]
	v_pk_mul_f32 v[40:41], v[30:31], v[40:41] op_sel_hi:[0,1]
	v_pk_mul_f32 v[34:35], v[30:31], v[34:35] op_sel_hi:[0,1]
	v_pk_mul_f32 v[36:37], v[30:31], v[36:37] op_sel_hi:[0,1]
	v_pk_mul_f32 v[26:27], v[30:31], v[26:27] op_sel_hi:[0,1]
	v_pk_mul_f32 v[28:29], v[30:31], v[28:29] op_sel_hi:[0,1]
	v_mad_i64_i32 v[32:33], s[20:21], v31, s22, v[98:99]
	v_cvt_pk_bf16_f32 v42, v42, v43
	v_cvt_pk_bf16_f32 v43, v44, v45
	v_cvt_pk_bf16_f32 v38, v38, v39
	v_cvt_pk_bf16_f32 v39, v40, v41
	v_cvt_pk_bf16_f32 v34, v34, v35
	v_cvt_pk_bf16_f32 v35, v36, v37
	v_cvt_pk_bf16_f32 v26, v26, v27
	v_cvt_pk_bf16_f32 v27, v28, v29
	global_store_dwordx2 v[32:33], v[42:43], off
	global_store_dwordx2 v[32:33], v[38:39], off offset:32
	global_store_dwordx2 v[32:33], v[34:35], off offset:64
	global_store_dwordx2 v[32:33], v[26:27], off offset:96
	s_mov_b64 s[20:21], 0x18000
	s_add_i32 s40, s40, 16
	v_mov_b64_e32 v[32:33], v[24:25]
	v_mov_b64_e32 v[28:29], v[20:21]
	v_lshl_add_u64 v[100:101], v[100:101], 0, s[20:21]
	s_cmp_lg_u32 s40, 64
	v_mov_b64_e32 v[30:31], v[22:23]
	v_mov_b64_e32 v[26:27], v[18:19]
	s_cbranch_scc0 .LBB0_323

; #define LAS __attribute__((address_space(3)))
; DI void ssd_item(const Params& p, const Ctx& c, int l, int S, int tokbase, int dir, int head) {
;     ...
;         __syncthreads();
;         if (tid < 384) {
; #pragma unroll
;             for (int q2 = 0; q2 < 4; ++q2) {
;                 const u32x4 va = raw[2 * q2], vb = raw[2 * q2 + 1];
;                 const int ra = dir ? 127 - (rg * 8 + 2 * q2) : rg * 8 + 2 * q2, rb = dir ? ra - 1 : ra + 1, rlo = dir ? rb : ra;
;                 const u32x4 vlo = dir ? vb : va, vhi = dir ? va : vb;
;                 const unsigned lo4[4] = {vlo.x, vlo.y, vlo.z, vlo.w}, hi4[4] = {vhi.x, vhi.y, vhi.z, vhi.w};
;                 if (part < 8) {
; #pragma unroll
;                     for (int j = 0; j < 4; ++j) { *(LAS unsigned*)(XT + (part * 8 + 2 * j) * MP + rlo) = (lo4[j] & 0xffffu) | (hi4[j] << 16);
;                         *(LAS unsigned*)(XT + (part * 8 + 2 * j + 1) * MP + rlo) = (lo4[j] >> 16) | (hi4[j] & 0xffff0000u); }
;                 } else if (part < 16) {
;                     *(LAS u32x4*)(Bs + ra * SP + (part - 8) * 8) = va; *(LAS u32x4*)(Bs + rb * SP + (part - 8) * 8) = vb;
; #pragma unroll
;                     for (int j = 0; j < 4; ++j) { *(LAS unsigned*)(BT + ((part - 8) * 8 + 2 * j) * MP + rlo) = (lo4[j] & 0xffffu) | (hi4[j] << 16);
;                         *(LAS unsigned*)(BT + ((part - 8) * 8 + 2 * j + 1) * MP + rlo) = (lo4[j] >> 16) | (hi4[j] & 0xffff0000u); }
;                 } else { *(LAS u32x4*)(Cs + ra * SP + (part - 16) * 8) = va; *(LAS u32x4*)(Cs + rb * SP + (part - 16) * 8) = vb; }
;             }
;         }
.LBB0_364:
	s_waitcnt lgkmcnt(0)
	s_barrier
	s_and_saveexec_b64 s[40:41], s[46:47]
	s_cbranch_execz .LBB0_397
	s_waitcnt vmcnt(4)
	v_cndmask_b32_e64 v1, v7, v11, s[44:45]
	v_cndmask_b32_e64 v3, v6, v10, s[44:45]
	v_cndmask_b32_e64 v44, v5, v9, s[44:45]
	v_cndmask_b32_e64 v46, v4, v8, s[44:45]
	v_cndmask_b32_e64 v2, v11, v7, s[44:45]
	v_cndmask_b32_e64 v45, v10, v6, s[44:45]
	v_cndmask_b32_e64 v47, v9, v5, s[44:45]
	v_cndmask_b32_e64 v48, v8, v4, s[44:45]
	s_and_saveexec_b64 s[24:25], s[42:43]
	s_xor_b64 s[70:71], exec, s[24:25]
	s_cbranch_execz .LBB0_371
	s_and_saveexec_b64 s[24:25], s[48:49]
	s_xor_b64 vcc, exec, s[24:25]
	s_cbranch_execz .LBB0_368
	v_add_u32_e32 v1, v83, v92
	ds_write_b128 v1, v[4:7] offset:18176
	v_add_u32_e32 v1, v83, v93
	ds_write_b128 v1, v[8:11] offset:18176

; #define SD_DLOAD(chx) do { const int tlo_ = dir ? S - 128 * ((chx) + 1) : 128 * (chx), t0_ = tlo_ + rg * 8; \
;         _Pragma("unroll") for (int q = 0; q < 8; ++q) { raw[q] = (u32x4){0u, 0u, 0u, 0u}; \
;             if (tid < 384) raw[q] = *(const u32x4*)(Pb + (size_t)(t0_ + q) * 768 + gcol); } } while (0)
; DI void ssd_item(const Params& p, const Ctx& c, int l, int S, int tokbase, int dir, int head) {
;     ...
;         __syncthreads();
;         if (ch + 1 < nch) SD_DLOAD(ch + 1);
.LBB0_397:
	s_or_b64 exec, exec, s[40:41]
	s_add_i32 s24, s2, 1
	s_cmp_ge_u32 s24, s34
	s_cselect_b64 s[40:41], -1, 0
	s_and_b64 vcc, exec, s[40:41]
	s_waitcnt lgkmcnt(0)
	s_barrier
	s_cbranch_vccnz .LBB0_415
	s_lshl_b32 s25, s2, 7
	s_sub_i32 s25, s95, s25
	s_lshl_b32 s26, s24, 7
	s_and_b64 s[70:71], s[44:45], exec
	s_waitcnt vmcnt(6)
	v_mov_b32_e32 v8, v0
	v_mov_b32_e32 v9, v0
	s_cselect_b32 s25, s26, s25
	v_mov_b32_e32 v10, v0
	v_mov_b32_e32 v11, v0
	v_mov_b64_e32 v[4:5], v[8:9]
	v_or_b32_e32 v44, s25, v76
	v_mov_b64_e32 v[6:7], v[10:11]
	s_and_saveexec_b64 s[70:71], s[46:47]
	s_cbranch_execz .LBB0_400
	v_mad_i64_i32 v[2:3], s[84:85], v44, s28, v[68:69]
	global_load_dwordx4 v[4:7], v[2:3], off

; DI float bf2f(unsigned h) { return __uint_as_float(h << 16); }
; DI unsigned pk2(float lo, float hi) { const f2_t v = {lo, hi}; const bf2_t r = __builtin_convertvector(v, bf2_t); return __builtin_bit_cast(unsigned, r); }
;     DI bf16_t* fOUTS() const { return (bf16_t*)(ws + WS_OUTS); }
; DI void ssd_item(const Params& p, const Ctx& c, int l, int S, int tokbase, int dir, int head) {
;     ...
;         {
;             const int sidx = ch * 128 + w * 16 + lr, tok = dir ? S - 1 - sidx : sidx;
;             bf16_t* op = c.fOUTS() + (size_t)(tokbase + tok) * OLD + 1536 + dir * 512 + head * 64 + lg * 4;
; #pragma unroll
;             for (int pt = 0; pt < 4; ++pt) { float y[4];
; #pragma unroll
;                 for (int r = 0; r < 4; ++r) { y[r] = accY[pt][r]; if (dir == 0) y[r] += dsk * bf2f((unsigned)XT[(pt * 16 + lg * 4 + r) * MP + w * 16 + lr]); }
;                 u32x2 o; o.x = pk2(y[0], y[1]); o.y = pk2(y[2], y[3]); *(u32x2*)(op + pt * 16) = o; }
.Lssd_out:
	s_and_b64 vcc, exec, s[44:45]
	s_cbranch_vccz .LBB0_421
	ds_read_u16 v114, v90
	ds_read_u16 v115, v89 offset:54544
	ds_read_u16 v116, v89 offset:54816
	ds_read_u16 v117, v89 offset:55088
	ds_read_u16 v118, v89 offset:58624
	ds_read_u16 v119, v89 offset:58896
	ds_read_u16 v120, v89 offset:59168
	ds_read_u16 v121, v89 offset:59440
	ds_read_u16 v122, v89 offset:62976
	ds_read_u16 v123, v89 offset:63248
	ds_read_u16 v124, v89 offset:63520
	ds_read_u16 v125, v89 offset:63792
	ds_read_u16 v126, v90 offset:13056
	ds_read_u16 v127, v90 offset:13328
	ds_read_u16 v128, v90 offset:13600
	ds_read_u16 v129, v90 offset:13872
	s_waitcnt lgkmcnt(0)
	v_lshlrev_b32_e32 v114, 16, v114
	v_lshlrev_b32_e32 v115, 16, v115
	v_lshlrev_b32_e32 v116, 16, v116
	v_lshlrev_b32_e32 v117, 16, v117
	v_lshlrev_b32_e32 v118, 16, v118
	v_lshlrev_b32_e32 v119, 16, v119
	v_lshlrev_b32_e32 v120, 16, v120
	v_lshlrev_b32_e32 v121, 16, v121
	v_lshlrev_b32_e32 v122, 16, v122
	v_lshlrev_b32_e32 v123, 16, v123
	v_lshlrev_b32_e32 v124, 16, v124
	v_lshlrev_b32_e32 v125, 16, v125
	v_lshlrev_b32_e32 v126, 16, v126
	v_lshlrev_b32_e32 v127, 16, v127
	v_lshlrev_b32_e32 v128, 16, v128
	v_lshlrev_b32_e32 v129, 16, v129
	v_fmac_f32_e32 v56, v75, v114
	v_fmac_f32_e32 v57, v75, v115
	v_fmac_f32_e32 v58, v75, v116
	v_fmac_f32_e32 v59, v75, v117
	v_fmac_f32_e32 v52, v75, v118
	v_fmac_f32_e32 v53, v75, v119
	v_fmac_f32_e32 v54, v75, v120
	v_fmac_f32_e32 v55, v75, v121
	v_fmac_f32_e32 v48, v75, v122
	v_fmac_f32_e32 v49, v75, v123
	v_fmac_f32_e32 v50, v75, v124
	v_fmac_f32_e32 v51, v75, v125
	v_fmac_f32_e32 v44, v75, v126
	v_fmac_f32_e32 v45, v75, v127
	v_fmac_f32_e32 v46, v75, v128
	v_fmac_f32_e32 v47, v75, v129
; DI float bf2f(unsigned h) { return __uint_as_float(h << 16); }
; DI unsigned pk2(float lo, float hi) { const f2_t v = {lo, hi}; const bf2_t r = __builtin_convertvector(v, bf2_t); return __builtin_bit_cast(unsigned, r); }
;     DI bf16_t* fOUTS() const { return (bf16_t*)(ws + WS_OUTS); }
; #define SD_GLOAD(chx) do { const int s0_ = (chx) * 128 + 2 * lane, t0_ = dir ? S - 1 - s0_ : s0_, t1_ = dir ? t0_ - 1 : t0_ + 1; gd0 = Sb[(size_t)t0_ * 32]; gd1 = Sb[(size_t)t1_ * 32]; } while (0)
; DI void ssd_item(const Params& p, const Ctx& c, int l, int S, int tokbase, int dir, int head) {
;     ...
;         {
;             const int sidx = ch * 128 + w * 16 + lr, tok = dir ? S - 1 - sidx : sidx;
;             bf16_t* op = c.fOUTS() + (size_t)(tokbase + tok) * OLD + 1536 + dir * 512 + head * 64 + lg * 4;
; #pragma unroll
;             for (int pt = 0; pt < 4; ++pt) { float y[4];
; #pragma unroll
;                 for (int r = 0; r < 4; ++r) { y[r] = accY[pt][r]; if (dir == 0) y[r] += dsk * bf2f((unsigned)XT[(pt * 16 + lg * 4 + r) * MP + w * 16 + lr]); }
;                 u32x2 o; o.x = pk2(y[0], y[1]); o.y = pk2(y[2], y[3]); *(u32x2*)(op + pt * 16) = o; }
;         }
;         if (w == 0 && ch + 1 < nch) { SD_PREP(par ^ 1); if (ch + 2 < nch) SD_GLOAD(ch + 2); }
.LBB0_421:
	v_lshl_add_u32 v1, s2, 7, v85
	v_xad_u32 v2, v1, -1, s30
	v_cndmask_b32_e64 v1, v2, v1, s[44:45]
	v_add_u32_e32 v1, s36, v1
	v_mov_b64_e32 v[2:3], s[92:93]
	v_mad_i64_i32 v[2:3], s[84:85], v1, s22, v[2:3]
	v_lshl_add_u64 v[2:3], v[2:3], 0, s[74:75]
	s_mov_b32 s81, s75
	v_lshl_add_u64 v[2:3], v[2:3], 0, s[80:81]
	v_mov_b32_e32 v73, v0
	v_lshl_add_u64 v[2:3], v[2:3], 0, v[72:73]
	v_cvt_pk_bf16_f32 v56, v56, v57
	v_cvt_pk_bf16_f32 v57, v58, v59
	v_add_co_u32_e32 v58, vcc, 0x10400000, v2
	s_nop 1
	v_addc_co_u32_e32 v59, vcc, 0, v3, vcc
	global_store_dwordx2 v[58:59], v[56:57], off offset:3072
	s_mov_b64 s[84:85], 0x10400c00
	v_lshl_add_u64 v[2:3], v[2:3], 0, s[84:85]
	v_cvt_pk_bf16_f32 v52, v52, v53
	v_cvt_pk_bf16_f32 v53, v54, v55
	global_store_dwordx2 v[2:3], v[52:53], off offset:32
	v_cvt_pk_bf16_f32 v48, v48, v49
	v_cvt_pk_bf16_f32 v49, v50, v51
	global_store_dwordx2 v[2:3], v[48:49], off offset:64
	s_or_b64 s[40:41], s[86:87], s[40:41]
	s_xor_b32 s26, s26, 1
	v_cvt_pk_bf16_f32 v44, v44, v45
	v_cvt_pk_bf16_f32 v45, v46, v47
	s_and_b64 vcc, exec, s[40:41]
	global_store_dwordx2 v[2:3], v[44:45], off offset:96
	s_cbranch_vccnz .LBB0_363
	s_waitcnt vmcnt(5)
	v_add_f32_e32 v2, v74, v79
	s_mov_b32 s40, 0x41a00000
	v_cmp_nlt_f32_e32 vcc, s40, v2
	s_and_saveexec_b64 s[40:41], vcc
	s_cbranch_execz .LBB0_439
	v_mul_f32_e32 v1, 0x3fb8aa3b, v2
	v_exp_f32_e32 v1, v1
	s_mov_b32 s70, 0x3f2aaaab
	v_add_f32_e32 v44, 1.0, v1
	v_frexp_mant_f32_e32 v46, v44
	v_cvt_f64_f32_e32 v[2:3], v44
	v_frexp_exp_i32_f64_e32 v2, v[2:3]
	v_cmp_gt_f32_e32 vcc, s70, v46
	v_add_f32_e32 v45, -1.0, v44
	v_sub_f32_e32 v47, v45, v44
	v_subbrev_co_u32_e32 v50, vcc, 0, v2, vcc
	v_sub_u32_e32 v2, 0, v50
	v_sub_f32_e32 v45, v1, v45
	v_add_f32_e32 v47, 1.0, v47
	v_ldexp_f32 v3, v44, v2
	v_add_f32_e32 v45, v45, v47
	v_add_f32_e32 v44, -1.0, v3
	v_add_f32_e32 v46, 1.0, v3
	v_ldexp_f32 v2, v45, v2
	v_add_f32_e32 v45, 1.0, v44
	v_add_f32_e32 v47, -1.0, v46
	v_sub_f32_e32 v45, v3, v45
	v_sub_f32_e32 v3, v3, v47
	v_add_f32_e32 v45, v2, v45
	v_add_f32_e32 v2, v2, v3
	v_add_f32_e32 v51, v46, v2
	v_rcp_f32_e32 v53, v51
	v_sub_f32_e32 v3, v51, v46
	v_sub_f32_e32 v52, v2, v3
	v_add_f32_e32 v3, v44, v45
	v_mul_f32_e32 v55, v3, v53
	v_sub_f32_e32 v2, v3, v44
	v_mul_f32_e32 v44, v51, v55
	v_fma_f32 v46, v55, v51, -v44
	v_fmac_f32_e32 v46, v55, v52
	v_sub_f32_e32 v54, v45, v2
	v_add_f32_e32 v2, v44, v46
	v_sub_f32_e32 v45, v3, v2
	v_pk_add_f32 v[48:49], v[2:3], v[44:45] neg_lo:[0,1] neg_hi:[0,1]
	v_mov_b32_e32 v47, v2
	v_pk_add_f32 v[2:3], v[48:49], v[46:47] neg_lo:[0,1] neg_hi:[0,1]
	s_mov_b32 s70, 0x3f317218
	v_add_f32_e32 v3, v54, v3
	v_add_f32_e32 v2, v2, v3
	v_add_f32_e32 v3, v45, v2
	v_mul_f32_e32 v54, v53, v3
	v_mul_f32_e32 v44, v51, v54
	v_fma_f32 v46, v54, v51, -v44
	v_fmac_f32_e32 v46, v54, v52
	v_sub_f32_e32 v45, v45, v3
	v_add_f32_e32 v51, v2, v45
	v_add_f32_e32 v2, v44, v46
	v_sub_f32_e32 v45, v3, v2
	v_pk_add_f32 v[48:49], v[2:3], v[44:45] neg_lo:[0,1] neg_hi:[0,1]
	v_mov_b32_e32 v47, v2
	v_pk_add_f32 v[2:3], v[48:49], v[46:47] neg_lo:[0,1] neg_hi:[0,1]
	v_cmp_neq_f32_e32 vcc, s5, v1
	v_add_f32_e32 v3, v51, v3
	v_add_f32_e32 v2, v2, v3
	v_add_f32_e32 v3, v55, v54
	v_add_f32_e32 v2, v45, v2
	v_sub_f32_e32 v44, v3, v55
	v_mul_f32_e32 v2, v53, v2
	v_sub_f32_e32 v44, v54, v44
	v_add_f32_e32 v44, v44, v2
	v_add_f32_e32 v46, v3, v44
	v_mul_f32_e32 v47, v46, v46
	v_fmamk_f32 v2, v47, 0x3e9b6dac, v166
	v_fmaak_f32 v173, v47, v2, 0x3f2aaada
	v_cvt_f32_i32_e32 v2, v50
	v_sub_f32_e32 v3, v46, v3
	v_sub_f32_e32 v3, v44, v3
	v_ldexp_f32 v48, v3, 1
	v_mul_f32_e32 v3, v46, v47
	v_ldexp_f32 v45, v46, 1
	v_pk_mul_f32 v[46:47], v[2:3], v[172:173]
	s_nop 0
	v_fma_f32 v44, v2, s70, -v46
	v_fmac_f32_e32 v44, 0xb102e308, v2
	v_pk_add_f32 v[2:3], v[46:47], v[44:45]
	s_nop 0
	v_sub_f32_e32 v45, v3, v45
	v_sub_f32_e32 v45, v47, v45
	v_add_f32_e32 v49, v48, v45
	v_mov_b32_e32 v48, v46
	v_pk_add_f32 v[46:47], v[2:3], v[46:47] neg_lo:[0,1] neg_hi:[0,1]
	v_pk_add_f32 v[50:51], v[2:3], v[48:49]
	v_mov_b32_e32 v45, v2
	v_mov_b32_e32 v47, v51
	v_pk_add_f32 v[52:53], v[44:45], v[46:47] neg_lo:[0,1] neg_hi:[0,1]
	v_pk_add_f32 v[44:45], v[44:45], v[46:47]
	v_mov_b32_e32 v48, v49
	v_pk_add_f32 v[46:47], v[44:45], v[2:3] op_sel:[1,0] op_sel_hi:[0,1] neg_lo:[0,1] neg_hi:[0,1]
	v_pk_add_f32 v[54:55], v[50:51], v[46:47] op_sel_hi:[1,0] neg_lo:[0,1] neg_hi:[0,1]
	v_mov_b32_e32 v50, v51
	v_mov_b32_e32 v51, v45
	v_pk_mov_b32 v[46:47], v[2:3], v[46:47] op_sel:[1,0]
	v_mov_b32_e32 v49, v2
	v_pk_add_f32 v[46:47], v[50:51], v[46:47] neg_lo:[0,1] neg_hi:[0,1]
	v_mov_b32_e32 v54, v52
	v_pk_add_f32 v[2:3], v[48:49], v[46:47] neg_lo:[0,1] neg_hi:[0,1]
	v_mov_b32_e32 v53, v45
	v_pk_add_f32 v[46:47], v[54:55], v[2:3]
	s_nop 0
	v_pk_add_f32 v[48:49], v[46:47], v[46:47] op_sel:[0,1] op_sel_hi:[1,0]
	s_nop 0
	v_pk_add_f32 v[44:45], v[44:45], v[48:49] op_sel:[1,0] op_sel_hi:[0,1]
	v_mov_b32_e32 v47, v44
	v_pk_add_f32 v[50:51], v[46:47], v[52:53] neg_lo:[0,1] neg_hi:[0,1]
	v_mov_b32_e32 v3, v48
	v_sub_f32_e32 v45, v46, v50
	v_pk_add_f32 v[2:3], v[2:3], v[50:51] neg_lo:[0,1] neg_hi:[0,1]
	v_sub_f32_e32 v45, v52, v45
	v_add_f32_e32 v2, v2, v45
	v_add_f32_e32 v2, v2, v3
	v_add_f32_e32 v2, v44, v2
	v_cndmask_b32_e32 v2, v209, v2, vcc
	v_cmp_ngt_f32_e32 vcc, -1.0, v1
	s_nop 1
	v_cndmask_b32_e32 v2, v210, v2, vcc
	v_cmp_neq_f32_e32 vcc, -1.0, v1
	s_nop 1
	v_cndmask_b32_e32 v2, v208, v2, vcc
	v_cmp_lt_f32_e64 vcc, |v1|, s27
	s_nop 1
	v_cndmask_b32_e32 v2, v2, v1, vcc

; #define LAS __attribute__((address_space(3)))
; DI u32x4 pack8(const float* f) { u32x4 w; w.x = pk2(f[0], f[1]); w.y = pk2(f[2], f[3]); w.z = pk2(f[4], f[5]); w.w = pk2(f[6], f[7]); return w; }
; DI void ssd_item(const Params& p, const Ctx& c, int l, int S, int tokbase, int dir, int head) {
;     ...
; #pragma unroll 1
;         for (int pp = 0; pp <= (w >> 1); ++pp) {
;             const int st0 = 2 * pp, st1 = st0 + 1;
;             bf16x8 b0f[2], b1f[2]; s16x4 xlo[4], xhi[4];
; #pragma unroll
;             for (int kk = 0; kk < 2; ++kk) { b0f[kk] = *(const LAS bf16x8*)(Bs + (st0 * 16 + lr) * SP + kk * 32 + lg * 8); b1f[kk] = *(const LAS bf16x8*)(Bs + (st1 * 16 + lr) * SP + kk * 32 + lg * 8); }
;             const f32x4 a0 = *(const LAS f32x4*)(G + st0 * 16 + lg * 4), a1 = *(const LAS f32x4*)(G + st1 * 16 + lg * 4);
;             const f32x4 d0 = *(const LAS f32x4*)(G + 128 + st0 * 16 + lg * 4), d1 = *(const LAS f32x4*)(G + 128 + st1 * 16 + lg * 4);
; #pragma unroll
;             for (int pt = 0; pt < 4; ++pt) { xlo[pt] = *(const LAS s16x4*)(XT + (pt * 16 + lr) * MP + st0 * 16 + lg * 4); xhi[pt] = *(const LAS s16x4*)(XT + (pt * 16 + lr) * MP + st1 * 16 + lg * 4); }
;             __builtin_amdgcn_sched_barrier(0);
;             f32x4 g0 = (f32x4){0.f, 0.f, 0.f, 0.f}, g1 = (f32x4){0.f, 0.f, 0.f, 0.f};
; #pragma unroll
;             for (int kk = 0; kk < 2; ++kk) { g0 = __builtin_amdgcn_mfma_f32_16x16x32_bf16(b0f[kk], cf[kk], g0, 0, 0, 0); g1 = __builtin_amdgcn_mfma_f32_16x16x32_bf16(b1f[kk], cf[kk], g1, 0, 0, 0); }
;             float g[8];
; #pragma unroll
;             for (int r = 0; r < 4; ++r) {
;                 float v0 = g0[r] * __expf(acsi - a0[r]) * d0[r], v1 = g1[r] * __expf(acsi - a1[r]) * d1[r];
;                 if (st0 == w && (lg * 4 + r) > lr) v0 = 0.f;
;                 if (st1 >= w && ((st1 > w) || (lg * 4 + r) > lr)) v1 = 0.f;
;                 g[r] = v0; g[4 + r] = v1; }
;             const bf16x8 bfr = __builtin_bit_cast(bf16x8, pack8(g));
; #pragma unroll
;             for (int pt = 0; pt < 4; ++pt) accY[pt] = __builtin_amdgcn_mfma_f32_16x16x32_bf16(__builtin_shufflevector(xlo[pt], xhi[pt], 0, 1, 2, 3, 4, 5, 6, 7), bfr, accY[pt], 0, 0, 0);
;         }
.LBB0_446:
	v_add_u32_e32 v113, 0, v3
	ds_read_b128 v[114:117], v113
	ds_read_b128 v[118:121], v113 offset:64
	ds_read_b128 v[122:125], v113 offset:2304
	ds_read_b128 v[126:129], v113 offset:2368
	v_add_u32_e32 v113, 0, v2
	v_add_u32_e32 v130, 0x16000, v113
	v_add_u32_e32 v134, 0x16040, v113
	v_add_u32_e32 v138, 0x16200, v113
	v_add_u32_e32 v113, 0x16240, v113
	ds_read_b128 v[130:133], v130
	ds_read_b128 v[134:137], v134
	ds_read_b128 v[138:141], v138
	ds_read_b128 v[142:145], v113
	v_add_u32_e32 v113, 0, v73
	v_add_u32_e32 v146, 0xd000, v113
	v_add_u32_e32 v150, 0xe000, v113
	v_add_u32_e32 v154, 0xf000, v113
	v_add_u32_e32 v158, 0x10700, v113
	ds_read2_b64 v[146:149], v146 offset0:128 offset1:132
	ds_read2_b64 v[150:153], v150 offset0:160 offset1:164
	ds_read2_b64 v[154:157], v154 offset0:192 offset1:196
	v_add_u32_e32 v113, 0x10720, v113
	ds_read_b64 v[158:159], v158
	ds_read_b64 v[160:161], v113
	s_add_i32 s81, s70, 1
	s_waitcnt lgkmcnt(12)
	v_mfma_f32_16x16x32_bf16 v[114:117], v[114:117], v[60:63], 0
	s_waitcnt lgkmcnt(8)
	v_sub_f32_e32 v113, v1, v130
	s_waitcnt lgkmcnt(7)
	v_sub_f32_e32 v130, v1, v134
	v_sub_f32_e32 v131, v1, v131
	v_mfma_f32_16x16x32_bf16 v[122:125], v[122:125], v[60:63], 0
	v_mul_f32_e32 v113, 0x3fb8aa3b, v113
	v_sub_f32_e32 v134, v1, v135
	v_sub_f32_e32 v135, v1, v136
	v_sub_f32_e32 v133, v1, v133
	v_sub_f32_e32 v136, v1, v137
	v_mul_f32_e32 v130, 0x3fb8aa3b, v130
	v_mul_f32_e32 v131, 0x3fb8aa3b, v131
	v_exp_f32_e32 v113, v113
	v_mfma_f32_16x16x32_bf16 v[114:117], v[118:121], v[64:67], v[114:117]
	v_mul_f32_e32 v134, 0x3fb8aa3b, v134
	v_mul_f32_e32 v135, 0x3fb8aa3b, v135
	v_mul_f32_e32 v133, 0x3fb8aa3b, v133
	v_mul_f32_e32 v136, 0x3fb8aa3b, v136
	v_exp_f32_e32 v130, v130
	v_exp_f32_e32 v131, v131
	v_mfma_f32_16x16x32_bf16 v[118:121], v[126:129], v[64:67], v[122:125]
	s_cmp_eq_u32 s21, s70
	v_sub_f32_e32 v132, v1, v132
	v_exp_f32_e32 v134, v134
	v_exp_f32_e32 v135, v135
	v_exp_f32_e32 v133, v133
	v_exp_f32_e32 v136, v136
	s_cselect_b64 s[84:85], -1, 0
	s_cmp_lt_i32 s81, s21
	v_mul_f32_e32 v132, 0x3fb8aa3b, v132
	v_exp_f32_e32 v132, v132
	v_mul_f32_e32 v113, v113, v114
	s_cselect_b64 vcc, -1, 0
	s_cmp_ge_i32 s70, s21
	v_mul_f32_e32 v114, v130, v118
	v_mul_f32_e32 v115, v131, v115
	s_waitcnt lgkmcnt(6)
	v_mul_f32_e32 v113, v138, v113
	s_cselect_b64 s[90:91], -1, 0
	s_and_b64 s[96:97], s[84:85], s[52:53]
	v_mul_f32_e32 v118, v134, v119
	v_mul_f32_e32 v119, v135, v120
	v_mul_f32_e32 v117, v133, v117
	v_mul_f32_e32 v120, v136, v121
	s_waitcnt lgkmcnt(5)
	v_mul_f32_e32 v121, v142, v114
	v_mul_f32_e32 v114, v139, v115
	v_cndmask_b32_e64 v113, v113, 0, s[96:97]
	s_and_b64 s[96:97], s[84:85], s[54:55]
	v_mul_f32_e32 v117, v141, v117
	v_cndmask_b32_e64 v114, v114, 0, s[96:97]
	s_and_b64 s[96:97], s[84:85], s[56:57]
	s_and_b64 s[84:85], s[84:85], s[58:59]
	v_mul_f32_e32 v116, v132, v116
	v_cndmask_b32_e64 v117, v117, 0, s[84:85]
	s_or_b64 s[84:85], s[90:91], s[52:53]
	v_mul_f32_e32 v118, v143, v118
	v_mul_f32_e32 v115, v140, v116
	v_mul_f32_e32 v116, v144, v119
	v_mul_f32_e32 v119, v145, v120
	v_cndmask_b32_e64 v120, v121, 0, s[84:85]
	s_or_b64 s[84:85], s[90:91], s[54:55]
	v_cndmask_b32_e64 v122, v118, 0, s[84:85]
	s_or_b64 s[84:85], s[90:91], s[56:57]
	v_cndmask_b32_e64 v123, v116, 0, s[84:85]
	s_or_b64 s[84:85], s[90:91], s[58:59]
	v_cndmask_b32_e64 v115, v115, 0, s[96:97]
	v_cndmask_b32_e64 v124, v119, 0, s[84:85]
	v_cvt_pk_bf16_f32 v114, v113, v114
	v_cvt_pk_bf16_f32 v115, v115, v117
	v_cndmask_b32_e32 v113, v120, v121, vcc
	v_cndmask_b32_e32 v117, v122, v118, vcc
	v_cndmask_b32_e32 v118, v123, v116, vcc
	v_cndmask_b32_e32 v119, v124, v119, vcc
	v_cvt_pk_bf16_f32 v116, v113, v117
	v_cvt_pk_bf16_f32 v117, v118, v119
	s_add_i32 s71, s71, -1
	s_add_i32 s70, s70, 2
	s_waitcnt lgkmcnt(4)
	v_mfma_f32_16x16x32_bf16 v[56:59], v[146:149], v[114:117], v[56:59]
	v_add_u32_e32 v73, 64, v73
	v_add_u32_e32 v3, 0x1200, v3
	s_cmp_eq_u32 s71, 0
	s_waitcnt lgkmcnt(3)
	v_mfma_f32_16x16x32_bf16 v[52:55], v[150:153], v[114:117], v[52:55]
	v_add_u32_e32 v2, 0x80, v2
	s_waitcnt lgkmcnt(2)
	v_mfma_f32_16x16x32_bf16 v[48:51], v[154:157], v[114:117], v[48:51]
	s_waitcnt lgkmcnt(0)
	v_mfma_f32_16x16x32_bf16 v[44:47], v[158:161], v[114:117], v[44:47]
	s_cbranch_scc0 .LBB0_446
	s_mov_b32 s96, 0x54442d18
	s_mov_b32 s97, 0x401921fb
	s_branch .Lssd_out
